# combo: S5 prefix loads batched + census loads batched + SB flag reads via 2 ds_read_b128 + compress-stage-2 loads batched + GEMM last-4-MFMA past barrier
# speedup vs baseline: 1.0122x; 1.0052x over previous
.LBB0_266:
	v_mov_b64_e32 v[10:11], s[12:13]
	v_add_co_u32_e32 v18, vcc, 0xfffff000, v8
	global_load_dwordx4 v[76:79], v[10:11], off
	s_nop 0
	v_addc_co_u32_e32 v19, vcc, -1, v9, vcc
	global_load_dwordx4 v[80:83], v[10:11], off offset:16
	global_load_dwordx4 v[84:87], v[10:11], off offset:32
	global_load_dwordx4 v[88:91], v[10:11], off offset:48
	global_load_dword v41, v[18:19], off offset:-3840
	global_load_dword v42, v[18:19], off offset:-3584
	global_load_dword v43, v[18:19], off offset:-3328
	global_load_dword v44, v[18:19], off offset:-3072
	global_load_dword v45, v[18:19], off offset:-2816
	global_load_dword v46, v[18:19], off offset:-2560
	global_load_dword v47, v[18:19], off offset:-2304
	global_load_dword v48, v[18:19], off offset:-2048
	global_load_dword v49, v[18:19], off offset:-1792
	global_load_dword v50, v[18:19], off offset:-1536
	global_load_dword v51, v[18:19], off offset:-1280
	global_load_dword v52, v[18:19], off offset:-1024
	global_load_dword v53, v[18:19], off offset:-768
	global_load_dword v54, v[18:19], off offset:-512
	global_load_dword v55, v[18:19], off offset:-256
	global_load_dword v56, v[18:19], off
	global_load_dword v57, v[8:9], off offset:-3840
	global_load_dword v58, v[8:9], off offset:-3584
	global_load_dword v59, v[8:9], off offset:-3328
	global_load_dword v60, v[8:9], off offset:-3072
	global_load_dword v61, v[8:9], off offset:-2816
	global_load_dword v62, v[8:9], off offset:-2560
	global_load_dword v63, v[8:9], off offset:-2304
	global_load_dword v64, v[8:9], off offset:-2048
	global_load_dword v65, v[8:9], off offset:-1792
	global_load_dword v66, v[8:9], off offset:-1536
	global_load_dword v67, v[8:9], off offset:-1280
	global_load_dword v68, v[8:9], off offset:-1024
	global_load_dword v69, v[8:9], off offset:-768
	global_load_dword v70, v[8:9], off offset:-512
	global_load_dword v71, v[8:9], off offset:-256
	global_load_dword v72, v[8:9], off
	s_add_i32 s6, s6, 32
	s_add_u32 s12, s12, 64
	s_mov_b64 s[18:19], 0x2000
	s_addc_u32 s13, s13, 0
	s_cmpk_gt_u32 s6, 0x77
	s_waitcnt vmcnt(0) lgkmcnt(0)
	v_lshlrev_b32_e32 v92, 16, v76
	s_nop 0
	v_fmac_f32_e32 v0, v41, v92
	v_and_b32_e32 v92, 0xffff0000, v76
	v_lshlrev_b32_e32 v93, 16, v77
	s_nop 0
	v_pk_mul_f32 v[94:95], v[42:43], v[92:93]
	s_nop 0
	v_add_f32_e32 v0, v0, v94
	v_add_f32_e32 v0, v0, v95
	v_and_b32_e32 v92, 0xffff0000, v77
	v_lshlrev_b32_e32 v93, 16, v78
	s_nop 0
	v_pk_mul_f32 v[94:95], v[44:45], v[92:93]
	s_nop 0
	v_add_f32_e32 v0, v0, v94
	v_add_f32_e32 v0, v0, v95
	v_and_b32_e32 v92, 0xffff0000, v78
	v_lshlrev_b32_e32 v93, 16, v79
	s_nop 0
	v_pk_mul_f32 v[94:95], v[46:47], v[92:93]
	s_nop 0
	v_add_f32_e32 v0, v0, v94
	v_add_f32_e32 v0, v0, v95
	v_and_b32_e32 v92, 0xffff0000, v79
	s_nop 0
	v_fmac_f32_e32 v0, v48, v92
	v_lshlrev_b32_e32 v92, 16, v80
	s_nop 0
	v_fmac_f32_e32 v0, v49, v92
	v_and_b32_e32 v92, 0xffff0000, v80
	v_lshlrev_b32_e32 v93, 16, v81
	s_nop 0
	v_pk_mul_f32 v[94:95], v[50:51], v[92:93]
	s_nop 0
	v_add_f32_e32 v0, v0, v94
	v_add_f32_e32 v0, v0, v95
	v_and_b32_e32 v92, 0xffff0000, v81
	v_lshlrev_b32_e32 v93, 16, v82
	s_nop 0
	v_pk_mul_f32 v[94:95], v[52:53], v[92:93]
	s_nop 0
	v_add_f32_e32 v0, v0, v94
	v_add_f32_e32 v0, v0, v95
	v_and_b32_e32 v92, 0xffff0000, v82
	v_lshlrev_b32_e32 v93, 16, v83
	s_nop 0
	v_pk_mul_f32 v[94:95], v[54:55], v[92:93]
	s_nop 0
	v_add_f32_e32 v0, v0, v94
	v_add_f32_e32 v0, v0, v95
	v_and_b32_e32 v92, 0xffff0000, v83
	s_nop 0
	v_fmac_f32_e32 v0, v56, v92
	v_lshlrev_b32_e32 v92, 16, v84
	s_nop 0
	v_fmac_f32_e32 v0, v57, v92
	v_and_b32_e32 v92, 0xffff0000, v84
	v_lshlrev_b32_e32 v93, 16, v85
	s_nop 0
	v_pk_mul_f32 v[94:95], v[58:59], v[92:93]
	s_nop 0
	v_add_f32_e32 v0, v0, v94
	v_add_f32_e32 v0, v0, v95
	v_and_b32_e32 v92, 0xffff0000, v85
	v_lshlrev_b32_e32 v93, 16, v86
	s_nop 0
	v_pk_mul_f32 v[94:95], v[60:61], v[92:93]
	s_nop 0
	v_add_f32_e32 v0, v0, v94
	v_add_f32_e32 v0, v0, v95
	v_and_b32_e32 v92, 0xffff0000, v86
	v_lshlrev_b32_e32 v93, 16, v87
	s_nop 0
	v_pk_mul_f32 v[94:95], v[62:63], v[92:93]
	s_nop 0
	v_add_f32_e32 v0, v0, v94
	v_add_f32_e32 v0, v0, v95
	v_and_b32_e32 v92, 0xffff0000, v87
	s_nop 0
	v_fmac_f32_e32 v0, v64, v92
	v_lshlrev_b32_e32 v92, 16, v88
	s_nop 0
	v_fmac_f32_e32 v0, v65, v92
	v_and_b32_e32 v92, 0xffff0000, v88
	v_lshlrev_b32_e32 v93, 16, v89
	s_nop 0
	v_pk_mul_f32 v[94:95], v[66:67], v[92:93]
	s_nop 0
	v_add_f32_e32 v0, v0, v94
	v_add_f32_e32 v0, v0, v95
	v_and_b32_e32 v92, 0xffff0000, v89
	v_lshlrev_b32_e32 v93, 16, v90
	s_nop 0
	v_pk_mul_f32 v[94:95], v[68:69], v[92:93]
	s_nop 0
	v_add_f32_e32 v0, v0, v94
	v_add_f32_e32 v0, v0, v95
	v_and_b32_e32 v92, 0xffff0000, v90
	v_lshlrev_b32_e32 v93, 16, v91
	s_nop 0
	v_pk_mul_f32 v[94:95], v[70:71], v[92:93]
	s_nop 0
	v_add_f32_e32 v0, v0, v94
	v_add_f32_e32 v0, v0, v95
	v_and_b32_e32 v92, 0xffff0000, v91
	s_nop 0
	v_fmac_f32_e32 v0, v72, v92
	v_lshl_add_u64 v[8:9], v[8:9], 0, s[18:19]
	s_cbranch_scc0 .LBB0_266
	s_bfe_i32 s11, s10, 0x100001
	s_mulk_i32 s11, 0x8103
	s_lshr_b32 s6, s10, 1
	s_lshr_b32 s11, s11, 16
	s_add_i32 s11, s11, s6
	s_sext_i32_i16 s12, s11
	s_ashr_i32 s12, s12, 6
	s_bfe_u32 s11, s11, 0x1000f
	s_add_i32 s11, s12, s11
	s_mul_i32 s12, s11, 0x7f
	s_sub_i32 s18, s6, s12
	s_and_b32 s6, s10, 1
	s_add_i32 s10, s16, 0x7ef
	s_sext_i32_i16 s17, s11
	s_mov_b64 s[12:13], -1
	s_cmpk_gt_u32 s10, 0xfde
	s_sext_i32_i16 s10, s18
	s_cbranch_scc0 .LBB0_269
	s_lshl_b32 s11, s17, 1
	s_or_b32 s12, s11, s6
	s_ashr_i32 s13, s12, 31
	s_lshl_b64 s[12:13], s[12:13], 14
	s_ashr_i32 s11, s10, 31
	v_lshl_add_u64 v[2:3], v[4:5], 0, s[12:13]
	v_cvt_pk_bf16_f32 v1, v0, s0
	v_lshl_add_u64 v[2:3], s[10:11], 1, v[2:3]
	flat_store_short v[2:3], v1
	s_mov_b64 s[12:13], 0

.LBB0_788:
	s_or_b64 exec, exec, s[16:17]
	s_mulk_i32 s41, 0xba20
	s_add_i32 s16, s33, s41
	s_add_i32 s17, s16, 0x8c00
	v_mov_b32_e32 v32, s17
	v_mov_b32_e32 v33, s35
	s_add_i32 s17, s16, 0x8c04
	s_waitcnt lgkmcnt(0)
	s_barrier
	ds_read_b128 v[36:39], v32
	ds_read_b128 v[40:43], v32 offset:16
	s_waitcnt vmcnt(0) lgkmcnt(0)
	v_or3_b32 v34, v36, v37, v38
	v_or3_b32 v35, v39, v40, v41
	v_or3_b32 v34, v34, v42, v43
	v_or_b32_e32 v32, v34, v35
	s_nop 0
	v_readfirstlane_b32 s16, v32
	s_cmp_eq_u32 s16, 0
	s_cbranch_scc1 .LBB0_785
	s_cmp_lt_i32 s13, 1
	s_cbranch_scc1 .LBB0_791
	v_mad_u64_u32 v[32:33], s[16:17], s6, v210, v[56:57]
	v_lshl_add_u64 v[34:35], s[6:7], 1, v[58:59]
	flat_load_dwordx4 v[52:55], v[32:33]
	flat_load_dwordx4 v[48:51], v[34:35]

.LBB0_917:
	v_readlane_b32 s8, v251, 31
	v_readlane_b32 s9, v251, 32
	v_readlane_b32 s10, v249, 5
	s_waitcnt lgkmcnt(0)
	s_nop 4
	global_load_dword v0, v177, s[8:9] sc1
	v_readlane_b32 s8, v251, 33
	v_readlane_b32 s9, v251, 34
	s_nop 4
	global_load_dword v1, v177, s[8:9] sc1
	v_readlane_b32 s8, v251, 35
	v_readlane_b32 s9, v251, 36
	s_nop 4
	global_load_dword v2, v177, s[8:9] sc1
	v_readlane_b32 s8, v251, 37
	v_readlane_b32 s9, v251, 38
	s_nop 4
	global_load_dword v3, v177, s[8:9] sc1
	v_readlane_b32 s8, v251, 39
	v_readlane_b32 s9, v251, 40
	s_nop 4
	global_load_dword v4, v177, s[8:9] sc1
	v_readlane_b32 s8, v251, 41
	v_readlane_b32 s9, v251, 42
	s_nop 4
	global_load_dword v5, v177, s[8:9] sc1
	v_readlane_b32 s8, v251, 43
	v_readlane_b32 s9, v251, 44
	s_nop 4
	global_load_dword v6, v177, s[8:9] sc1
	v_readlane_b32 s8, v251, 45
	v_readlane_b32 s9, v251, 46
	s_nop 4
	global_load_dword v7, v177, s[8:9] sc1
	v_readlane_b32 s8, v251, 47
	v_readlane_b32 s9, v251, 48
	s_nop 4
	global_load_dword v8, v177, s[8:9] sc1
	v_readlane_b32 s8, v251, 49
	v_readlane_b32 s9, v251, 50
	s_nop 4
	global_load_dword v9, v177, s[8:9] sc1
	v_readlane_b32 s8, v251, 51
	v_readlane_b32 s9, v251, 52
	s_nop 4
	global_load_dword v10, v177, s[8:9] sc1
	v_readlane_b32 s8, v251, 53
	v_readlane_b32 s9, v251, 54
	s_nop 4
	global_load_dword v11, v177, s[8:9] sc1
	v_readlane_b32 s8, v251, 55
	v_readlane_b32 s9, v251, 56
	s_nop 4
	global_load_dword v12, v177, s[8:9] sc1
	v_readlane_b32 s8, v251, 57
	v_readlane_b32 s9, v251, 58
	s_nop 4
	global_load_dword v13, v177, s[8:9] sc1
	v_readlane_b32 s8, v251, 59
	v_readlane_b32 s9, v251, 60
	s_nop 4
	global_load_dword v14, v177, s[8:9] sc1
	v_readlane_b32 s8, v251, 61
	v_readlane_b32 s9, v251, 62
	s_nop 4
	global_load_dword v15, v177, s[8:9] sc1
	s_mov_b64 s[8:9], -1
	s_waitcnt vmcnt(0)
	v_add_u32_e32 v16, v1, v0
	v_add_u32_e32 v16, v16, v2
	v_add_u32_e32 v16, v16, v3
	v_add_u32_e32 v16, v16, v4
	v_add_u32_e32 v16, v16, v5
	v_add_u32_e32 v16, v16, v6
	v_add_u32_e32 v16, v16, v7
	v_add_u32_e32 v16, v16, v8
	v_add_u32_e32 v16, v16, v9
	v_add_u32_e32 v16, v16, v10
	v_add_u32_e32 v16, v16, v11
	v_add_u32_e32 v16, v16, v12
	v_add_u32_e32 v16, v16, v13
	v_add_u32_e32 v16, v16, v14
	v_add_u32_e32 v16, v16, v15
	v_cmp_eq_u32_e32 vcc, s10, v16
	s_mov_b64 s[10:11], -1
	s_cbranch_vccnz .LBB0_916
	s_and_b32 s8, s14, 0xff
	s_cmp_eq_u32 s8, 0
	s_mov_b64 s[8:9], -1
	s_mov_b64 s[12:13], -1
	s_sleep 1
	s_cbranch_scc1 .LBB0_921
	s_and_b64 vcc, exec, s[12:13]
	s_cbranch_vccz .LBB0_916
